# GEMM main loops: head select block and counter increments moved in front of the loop-back barrier (loop-edge rotation)
# baseline (speedup 1.0000x reference)
.Lrot_304:
	v_add_u32_e32 v110, s62, v227
	v_add_u32_e32 v126, s64, v227
	ds_read_b128 v[98:101], v110
	ds_read_b128 v[102:105], v110 offset:1024
	ds_read_b128 v[106:109], v110 offset:2048
	ds_read_b128 v[110:113], v110 offset:3072
	ds_read_b128 v[114:117], v126
	ds_read_b128 v[118:121], v126 offset:1024
	ds_read_b128 v[122:125], v126 offset:2048
	ds_read_b128 v[126:129], v126 offset:3072
	v_lshl_add_u64 v[210:211], s[22:23], 0, v[190:191]
	s_add_i32 m0, s47, 0xc000
	ds_read_b128 v[162:165], v228
	ds_read_b128 v[166:169], v228 offset:1024
	ds_read_b128 v[194:197], v228 offset:2048
	ds_read_b128 v[198:201], v228 offset:3072
	ds_read_b128 v[202:205], v228 offset:4096
	ds_read_b128 v[206:209], v228 offset:5120
	ds_read_b128 v[230:233], v228 offset:6144
	ds_read_b128 v[234:237], v228 offset:7168
	global_load_lds_dwordx4 v[210:211], off
	v_lshl_add_u64 v[210:211], s[22:23], 0, v[192:193]
	s_add_i32 m0, s47, 0xe000
	s_nop 0
	global_load_lds_dwordx4 v[210:211], off
	s_waitcnt vmcnt(8)
	s_waitcnt lgkmcnt(0)
	s_barrier
	s_setprio 1
	s_waitcnt lgkmcnt(0)
	v_mfma_f32_16x16x32_bf16 v[158:161], v[98:101], v[162:165], v[158:161]
	v_mfma_f32_16x16x32_bf16 v[154:157], v[106:109], v[162:165], v[154:157]
	v_mfma_f32_16x16x32_bf16 v[142:145], v[98:101], v[194:197], v[142:145]
	v_mfma_f32_16x16x32_bf16 v[138:141], v[106:109], v[194:197], v[138:141]
	v_mfma_f32_16x16x32_bf16 v[94:97], v[98:101], v[202:205], v[94:97]
	v_mfma_f32_16x16x32_bf16 v[90:93], v[106:109], v[202:205], v[90:93]
	v_mfma_f32_16x16x32_bf16 v[78:81], v[98:101], v[230:233], v[78:81]
	v_mfma_f32_16x16x32_bf16 v[74:77], v[106:109], v[230:233], v[74:77]
	v_mfma_f32_16x16x32_bf16 v[158:161], v[102:105], v[166:169], v[158:161]
	v_mfma_f32_16x16x32_bf16 v[154:157], v[110:113], v[166:169], v[154:157]
	v_mfma_f32_16x16x32_bf16 v[142:145], v[102:105], v[198:201], v[142:145]
	v_mfma_f32_16x16x32_bf16 v[138:141], v[110:113], v[198:201], v[138:141]
	v_mfma_f32_16x16x32_bf16 v[94:97], v[102:105], v[206:209], v[94:97]
	v_mfma_f32_16x16x32_bf16 v[90:93], v[110:113], v[206:209], v[90:93]
	v_mfma_f32_16x16x32_bf16 v[78:81], v[102:105], v[234:237], v[78:81]
	v_mfma_f32_16x16x32_bf16 v[74:77], v[110:113], v[234:237], v[74:77]
	s_setprio 0
	s_setprio 1
	v_mfma_f32_16x16x32_bf16 v[150:153], v[114:117], v[162:165], v[150:153]
	v_mfma_f32_16x16x32_bf16 v[146:149], v[122:125], v[162:165], v[146:149]
	v_mfma_f32_16x16x32_bf16 v[134:137], v[114:117], v[194:197], v[134:137]
	v_mfma_f32_16x16x32_bf16 v[130:133], v[122:125], v[194:197], v[130:133]
	v_mfma_f32_16x16x32_bf16 v[86:89], v[114:117], v[202:205], v[86:89]
	v_mfma_f32_16x16x32_bf16 v[82:85], v[122:125], v[202:205], v[82:85]
	v_mfma_f32_16x16x32_bf16 v[70:73], v[114:117], v[230:233], v[70:73]
	v_mfma_f32_16x16x32_bf16 v[66:69], v[122:125], v[230:233], v[66:69]
	v_mfma_f32_16x16x32_bf16 v[150:153], v[118:121], v[166:169], v[150:153]
	v_mfma_f32_16x16x32_bf16 v[146:149], v[126:129], v[166:169], v[146:149]
	v_mfma_f32_16x16x32_bf16 v[134:137], v[118:121], v[198:201], v[134:137]
	v_mfma_f32_16x16x32_bf16 v[130:133], v[126:129], v[198:201], v[130:133]
	v_mfma_f32_16x16x32_bf16 v[86:89], v[118:121], v[206:209], v[86:89]
	v_mfma_f32_16x16x32_bf16 v[82:85], v[126:129], v[206:209], v[82:85]
	v_mfma_f32_16x16x32_bf16 v[70:73], v[118:121], v[234:237], v[70:73]
	v_mfma_f32_16x16x32_bf16 v[66:69], v[126:129], v[234:237], v[66:69]
	s_setprio 0
	s_barrier
	s_add_i32 s62, s62, s46
	v_lshl_add_u64 v[210:211], s[24:25], 0, v[0:1]
	s_mov_b32 m0, s62
	ds_read_b128 v[162:165], v228 offset:16384
	ds_read_b128 v[166:169], v228 offset:17408
	ds_read_b128 v[194:197], v228 offset:18432
	ds_read_b128 v[198:201], v228 offset:19456
	ds_read_b128 v[202:205], v228 offset:20480
	ds_read_b128 v[206:209], v228 offset:21504
	ds_read_b128 v[230:233], v228 offset:22528
	ds_read_b128 v[234:237], v228 offset:23552
	global_load_lds_dwordx4 v[210:211], off
	s_add_i32 m0, s62, 0x2000
	s_add_u32 s62, s24, 0x40000
	v_lshl_add_u64 v[238:239], s[24:25], 0, v[184:185]
	s_addc_u32 s63, s25, 0
	s_add_i32 s64, s64, s46
	global_load_lds_dwordx4 v[238:239], off
	v_lshl_add_u64 v[240:241], s[62:63], 0, v[0:1]
	s_mov_b32 m0, s64
	v_lshl_add_u64 v[242:243], s[38:39], 0, v[186:187]
	global_load_lds_dwordx4 v[240:241], off
	v_lshl_add_u64 v[240:241], s[62:63], 0, v[184:185]
	s_add_i32 m0, s64, 0x2000
	s_nop 0
	global_load_lds_dwordx4 v[240:241], off
	v_lshl_add_u64 v[240:241], s[38:39], 0, v[188:189]
	s_mov_b32 m0, s47
	s_nop 0
	global_load_lds_dwordx4 v[240:241], off
	s_mov_b32 m0, s48
	s_nop 0
	global_load_lds_dwordx4 v[242:243], off
	s_waitcnt vmcnt(8)
	s_waitcnt lgkmcnt(0)
	s_barrier
	s_setprio 1
	s_waitcnt lgkmcnt(0)
	v_mfma_f32_16x16x32_bf16 v[62:65], v[98:101], v[162:165], v[62:65]
	v_mfma_f32_16x16x32_bf16 v[58:61], v[106:109], v[162:165], v[58:61]
	v_mfma_f32_16x16x32_bf16 v[46:49], v[98:101], v[194:197], v[46:49]
	v_mfma_f32_16x16x32_bf16 v[42:45], v[106:109], v[194:197], v[42:45]
	v_mfma_f32_16x16x32_bf16 v[30:33], v[98:101], v[202:205], v[30:33]
	v_mfma_f32_16x16x32_bf16 v[26:29], v[106:109], v[202:205], v[26:29]
	v_mfma_f32_16x16x32_bf16 v[14:17], v[98:101], v[230:233], v[14:17]
	v_mfma_f32_16x16x32_bf16 v[10:13], v[106:109], v[230:233], v[10:13]
	v_mfma_f32_16x16x32_bf16 v[62:65], v[102:105], v[166:169], v[62:65]
	v_mfma_f32_16x16x32_bf16 v[58:61], v[110:113], v[166:169], v[58:61]
	v_mfma_f32_16x16x32_bf16 v[46:49], v[102:105], v[198:201], v[46:49]
	v_mfma_f32_16x16x32_bf16 v[42:45], v[110:113], v[198:201], v[42:45]
	v_mfma_f32_16x16x32_bf16 v[30:33], v[102:105], v[206:209], v[30:33]
	v_mfma_f32_16x16x32_bf16 v[26:29], v[110:113], v[206:209], v[26:29]
	v_mfma_f32_16x16x32_bf16 v[14:17], v[102:105], v[234:237], v[14:17]
	v_mfma_f32_16x16x32_bf16 v[10:13], v[110:113], v[234:237], v[10:13]
	s_setprio 0
	s_setprio 1
	v_mfma_f32_16x16x32_bf16 v[54:57], v[114:117], v[162:165], v[54:57]
	v_mfma_f32_16x16x32_bf16 v[50:53], v[122:125], v[162:165], v[50:53]
	v_mfma_f32_16x16x32_bf16 v[38:41], v[114:117], v[194:197], v[38:41]
	v_mfma_f32_16x16x32_bf16 v[34:37], v[122:125], v[194:197], v[34:37]
	v_mfma_f32_16x16x32_bf16 v[22:25], v[114:117], v[202:205], v[22:25]
	v_mfma_f32_16x16x32_bf16 v[18:21], v[122:125], v[202:205], v[18:21]
	v_mfma_f32_16x16x32_bf16 v[6:9], v[114:117], v[230:233], v[6:9]
	v_mfma_f32_16x16x32_bf16 v[2:5], v[122:125], v[230:233], v[2:5]
	v_mfma_f32_16x16x32_bf16 v[54:57], v[118:121], v[166:169], v[54:57]
	v_mfma_f32_16x16x32_bf16 v[50:53], v[126:129], v[166:169], v[50:53]
	v_mfma_f32_16x16x32_bf16 v[38:41], v[118:121], v[198:201], v[38:41]
	v_mfma_f32_16x16x32_bf16 v[34:37], v[126:129], v[198:201], v[34:37]
	v_mfma_f32_16x16x32_bf16 v[22:25], v[118:121], v[206:209], v[22:25]
	v_mfma_f32_16x16x32_bf16 v[18:21], v[126:129], v[206:209], v[18:21]
	v_mfma_f32_16x16x32_bf16 v[6:9], v[118:121], v[234:237], v[6:9]
	v_mfma_f32_16x16x32_bf16 v[2:5], v[126:129], v[234:237], v[2:5]
	s_setprio 0
	s_barrier
	s_add_i32 s62, 0, 0x18000
	s_add_i32 s63, 0, 0x1c000
	v_add_u32_e32 v110, s62, v227
	v_add_u32_e32 v126, s63, v227
	ds_read_b128 v[98:101], v110
	ds_read_b128 v[102:105], v110 offset:1024
	ds_read_b128 v[106:109], v110 offset:2048
	ds_read_b128 v[110:113], v110 offset:3072
	ds_read_b128 v[114:117], v126
	ds_read_b128 v[118:121], v126 offset:1024
	ds_read_b128 v[122:125], v126 offset:2048
	ds_read_b128 v[126:129], v126 offset:3072
	s_add_u32 s38, s38, 0x40000
	s_addc_u32 s39, s39, 0
	s_mov_b32 m0, s49
	v_lshl_add_u64 v[244:245], s[38:39], 0, v[188:189]
	ds_read_b128 v[162:165], v228 offset:32768
	ds_read_b128 v[166:169], v228 offset:33792
	ds_read_b128 v[194:197], v228 offset:34816
	ds_read_b128 v[198:201], v228 offset:35840
	ds_read_b128 v[202:205], v228 offset:36864
	ds_read_b128 v[206:209], v228 offset:37888
	ds_read_b128 v[230:233], v228 offset:38912
	ds_read_b128 v[234:237], v228 offset:39936
	global_load_lds_dwordx4 v[244:245], off
	v_lshl_add_u64 v[244:245], s[38:39], 0, v[186:187]
	s_mov_b32 m0, s50
	s_nop 0
	global_load_lds_dwordx4 v[244:245], off
	s_waitcnt vmcnt(8)
	s_waitcnt lgkmcnt(0)
	s_barrier
	s_setprio 1
	s_waitcnt lgkmcnt(0)
	v_mfma_f32_16x16x32_bf16 v[158:161], v[98:101], v[162:165], v[158:161]
	v_mfma_f32_16x16x32_bf16 v[154:157], v[106:109], v[162:165], v[154:157]
	v_mfma_f32_16x16x32_bf16 v[142:145], v[98:101], v[194:197], v[142:145]
	v_mfma_f32_16x16x32_bf16 v[138:141], v[106:109], v[194:197], v[138:141]
	v_mfma_f32_16x16x32_bf16 v[94:97], v[98:101], v[202:205], v[94:97]
	v_mfma_f32_16x16x32_bf16 v[90:93], v[106:109], v[202:205], v[90:93]
	v_mfma_f32_16x16x32_bf16 v[78:81], v[98:101], v[230:233], v[78:81]
	v_mfma_f32_16x16x32_bf16 v[74:77], v[106:109], v[230:233], v[74:77]
	v_mfma_f32_16x16x32_bf16 v[158:161], v[102:105], v[166:169], v[158:161]
	v_mfma_f32_16x16x32_bf16 v[154:157], v[110:113], v[166:169], v[154:157]
	v_mfma_f32_16x16x32_bf16 v[142:145], v[102:105], v[198:201], v[142:145]
	v_mfma_f32_16x16x32_bf16 v[138:141], v[110:113], v[198:201], v[138:141]
	v_mfma_f32_16x16x32_bf16 v[94:97], v[102:105], v[206:209], v[94:97]
	v_mfma_f32_16x16x32_bf16 v[90:93], v[110:113], v[206:209], v[90:93]
	v_mfma_f32_16x16x32_bf16 v[78:81], v[102:105], v[234:237], v[78:81]
	v_mfma_f32_16x16x32_bf16 v[74:77], v[110:113], v[234:237], v[74:77]
	s_setprio 0
	s_setprio 1
	v_mfma_f32_16x16x32_bf16 v[150:153], v[114:117], v[162:165], v[150:153]
	v_mfma_f32_16x16x32_bf16 v[146:149], v[122:125], v[162:165], v[146:149]
	v_mfma_f32_16x16x32_bf16 v[134:137], v[114:117], v[194:197], v[134:137]
	v_mfma_f32_16x16x32_bf16 v[130:133], v[122:125], v[194:197], v[130:133]
	v_mfma_f32_16x16x32_bf16 v[86:89], v[114:117], v[202:205], v[86:89]
	v_mfma_f32_16x16x32_bf16 v[82:85], v[122:125], v[202:205], v[82:85]
	v_mfma_f32_16x16x32_bf16 v[70:73], v[114:117], v[230:233], v[70:73]
	v_mfma_f32_16x16x32_bf16 v[66:69], v[122:125], v[230:233], v[66:69]
	v_mfma_f32_16x16x32_bf16 v[150:153], v[118:121], v[166:169], v[150:153]
	v_mfma_f32_16x16x32_bf16 v[146:149], v[126:129], v[166:169], v[146:149]
	v_mfma_f32_16x16x32_bf16 v[134:137], v[118:121], v[198:201], v[134:137]
	v_mfma_f32_16x16x32_bf16 v[130:133], v[126:129], v[198:201], v[130:133]
	v_mfma_f32_16x16x32_bf16 v[86:89], v[118:121], v[206:209], v[86:89]
	v_mfma_f32_16x16x32_bf16 v[82:85], v[126:129], v[206:209], v[82:85]
	v_mfma_f32_16x16x32_bf16 v[70:73], v[118:121], v[234:237], v[70:73]
	v_mfma_f32_16x16x32_bf16 v[66:69], v[126:129], v[234:237], v[66:69]
	s_setprio 0
	s_barrier
	s_add_i32 s38, s62, s46
	v_lshl_add_u64 v[210:211], v[210:211], 0, s[14:15]
	s_mov_b32 m0, s38
	ds_read_b128 v[162:165], v228 offset:49152
	ds_read_b128 v[166:169], v228 offset:50176
	ds_read_b128 v[194:197], v228 offset:51200
	ds_read_b128 v[198:201], v228 offset:52224
	ds_read_b128 v[202:205], v228 offset:53248
	ds_read_b128 v[206:209], v228 offset:54272
	ds_read_b128 v[230:233], v228 offset:55296
	ds_read_b128 v[234:237], v228 offset:56320
	global_load_lds_dwordx4 v[210:211], off
	s_add_i32 m0, s38, 0x2000
	s_add_u32 s24, s24, 0x40080
	v_lshl_add_u64 v[210:211], v[238:239], 0, s[14:15]
	s_addc_u32 s25, s25, 0
	s_add_i32 s38, s63, s46
	global_load_lds_dwordx4 v[210:211], off
	v_lshl_add_u64 v[210:211], s[24:25], 0, v[0:1]
	s_mov_b32 m0, s38
	s_nop 0
	global_load_lds_dwordx4 v[210:211], off
	v_lshl_add_u64 v[210:211], s[24:25], 0, v[184:185]
	s_add_i32 m0, s38, 0x2000
	s_nop 0
	global_load_lds_dwordx4 v[210:211], off
	v_lshl_add_u64 v[210:211], v[240:241], 0, s[14:15]
	s_mov_b32 m0, s54
	s_nop 0
	global_load_lds_dwordx4 v[210:211], off
	v_lshl_add_u64 v[210:211], v[242:243], 0, s[14:15]
	s_mov_b32 m0, s55
	s_nop 0
	global_load_lds_dwordx4 v[210:211], off
	s_waitcnt vmcnt(8)
	s_waitcnt lgkmcnt(0)
	s_barrier
	s_setprio 1
	s_waitcnt lgkmcnt(0)
	v_mfma_f32_16x16x32_bf16 v[62:65], v[98:101], v[162:165], v[62:65]
	v_mfma_f32_16x16x32_bf16 v[58:61], v[106:109], v[162:165], v[58:61]
	v_mfma_f32_16x16x32_bf16 v[46:49], v[98:101], v[194:197], v[46:49]
	v_mfma_f32_16x16x32_bf16 v[42:45], v[106:109], v[194:197], v[42:45]
	v_mfma_f32_16x16x32_bf16 v[30:33], v[98:101], v[202:205], v[30:33]
	v_mfma_f32_16x16x32_bf16 v[26:29], v[106:109], v[202:205], v[26:29]
	v_mfma_f32_16x16x32_bf16 v[14:17], v[98:101], v[230:233], v[14:17]
	v_mfma_f32_16x16x32_bf16 v[10:13], v[106:109], v[230:233], v[10:13]
	v_mfma_f32_16x16x32_bf16 v[62:65], v[102:105], v[166:169], v[62:65]
	v_mfma_f32_16x16x32_bf16 v[58:61], v[110:113], v[166:169], v[58:61]
	v_mfma_f32_16x16x32_bf16 v[46:49], v[102:105], v[198:201], v[46:49]
	v_mfma_f32_16x16x32_bf16 v[42:45], v[110:113], v[198:201], v[42:45]
	v_mfma_f32_16x16x32_bf16 v[30:33], v[102:105], v[206:209], v[30:33]
	v_mfma_f32_16x16x32_bf16 v[26:29], v[110:113], v[206:209], v[26:29]
	v_mfma_f32_16x16x32_bf16 v[14:17], v[102:105], v[234:237], v[14:17]
	v_mfma_f32_16x16x32_bf16 v[10:13], v[110:113], v[234:237], v[10:13]
	s_setprio 0
	s_setprio 1
	v_mfma_f32_16x16x32_bf16 v[54:57], v[114:117], v[162:165], v[54:57]
	v_mfma_f32_16x16x32_bf16 v[50:53], v[122:125], v[162:165], v[50:53]
	v_mfma_f32_16x16x32_bf16 v[38:41], v[114:117], v[194:197], v[38:41]
	v_mfma_f32_16x16x32_bf16 v[34:37], v[122:125], v[194:197], v[34:37]
	v_mfma_f32_16x16x32_bf16 v[22:25], v[114:117], v[202:205], v[22:25]
	v_mfma_f32_16x16x32_bf16 v[18:21], v[122:125], v[202:205], v[18:21]
	v_mfma_f32_16x16x32_bf16 v[6:9], v[114:117], v[230:233], v[6:9]
	v_mfma_f32_16x16x32_bf16 v[2:5], v[122:125], v[230:233], v[2:5]
	v_mfma_f32_16x16x32_bf16 v[54:57], v[118:121], v[166:169], v[54:57]
	v_mfma_f32_16x16x32_bf16 v[50:53], v[126:129], v[166:169], v[50:53]
	v_mfma_f32_16x16x32_bf16 v[38:41], v[118:121], v[198:201], v[38:41]
	v_mfma_f32_16x16x32_bf16 v[34:37], v[126:129], v[198:201], v[34:37]
	v_mfma_f32_16x16x32_bf16 v[22:25], v[118:121], v[206:209], v[22:25]
	v_mfma_f32_16x16x32_bf16 v[18:21], v[126:129], v[206:209], v[18:21]
	v_mfma_f32_16x16x32_bf16 v[6:9], v[118:121], v[234:237], v[6:9]
	v_mfma_f32_16x16x32_bf16 v[2:5], v[126:129], v[234:237], v[2:5]
	s_setprio 0
	s_add_i32 s61, s61, 2
	s_add_u32 s22, s22, 0x100
	s_addc_u32 s23, s23, 0
	s_add_u32 s42, s42, 0x100
	s_addc_u32 s43, s43, 0
	s_add_u32 s24, s22, 0xfffc0080
	s_addc_u32 s25, s23, -1
	s_add_i32 s62, 0, 0x10000
	s_cmp_eq_u32 s61, 12
	s_cselect_b32 s39, s17, s25
	s_cselect_b32 s38, s40, s24
	s_cselect_b32 s25, s13, s43
	s_cselect_b32 s24, s41, s42
	s_add_i32 s64, 0, 0x14000
	s_barrier
	s_cmp_gt_u32 s61, 13
	s_cbranch_scc0 .Lrot_304
	s_and_b64 vcc, exec, s[10:11]
	s_cbranch_vccz .LBB0_307
	s_barrier

.LBB0_498:
	s_add_u32 s20, s18, 0xfffc0080
	s_addc_u32 s21, s19, -1
	s_add_i32 s41, 0, 0x10000
	s_cmp_eq_u32 s40, 12
	s_cselect_b32 s23, s9, s21
	s_cselect_b32 s22, s25, s20
	s_cselect_b32 s21, s11, s39
	s_cselect_b32 s20, s34, s38
	s_add_i32 s44, 0, 0x14000
.Lrot_498:
	v_add_u32_e32 v0, s41, v165
	ds_read_b128 v[142:145], v0
	ds_read_b128 v[146:149], v0 offset:1024
	ds_read_b128 v[150:153], v0 offset:2048
	ds_read_b128 v[154:157], v0 offset:3072
	v_add_u32_e32 v0, s44, v165
	ds_read_b128 v[160:163], v0
	ds_read_b128 v[184:187], v0 offset:1024
	ds_read_b128 v[188:191], v0 offset:2048
	ds_read_b128 v[192:195], v0 offset:3072
	v_lshl_add_u64 v[168:169], s[18:19], 0, v[138:139]
	s_add_i32 m0, s50, 0xc000
	ds_read_b128 v[196:199], v166
	ds_read_b128 v[200:203], v166 offset:1024
	ds_read_b128 v[204:207], v166 offset:2048
	ds_read_b128 v[208:211], v166 offset:3072
	ds_read_b128 v[226:229], v166 offset:4096
	ds_read_b128 v[230:233], v166 offset:5120
	ds_read_b128 v[234:237], v166 offset:6144
	ds_read_b128 v[238:241], v166 offset:7168
	global_load_lds_dwordx4 v[168:169], off
	v_lshl_add_u64 v[168:169], s[18:19], 0, v[140:141]
	s_add_i32 m0, s50, 0xe000
	s_nop 0
	global_load_lds_dwordx4 v[168:169], off
	s_waitcnt vmcnt(8)
	s_waitcnt lgkmcnt(0)
	s_barrier
	s_setprio 1
	s_waitcnt lgkmcnt(0)
	v_mfma_f32_16x16x32_bf16 v[126:129], v[142:145], v[196:199], v[126:129]
	v_mfma_f32_16x16x32_bf16 v[122:125], v[150:153], v[196:199], v[122:125]
	v_mfma_f32_16x16x32_bf16 v[110:113], v[142:145], v[204:207], v[110:113]
	v_mfma_f32_16x16x32_bf16 v[106:109], v[150:153], v[204:207], v[106:109]
	v_mfma_f32_16x16x32_bf16 v[94:97], v[142:145], v[226:229], v[94:97]
	v_mfma_f32_16x16x32_bf16 v[90:93], v[150:153], v[226:229], v[90:93]
	v_mfma_f32_16x16x32_bf16 v[78:81], v[142:145], v[234:237], v[78:81]
	v_mfma_f32_16x16x32_bf16 v[74:77], v[150:153], v[234:237], v[74:77]
	v_mfma_f32_16x16x32_bf16 v[126:129], v[146:149], v[200:203], v[126:129]
	v_mfma_f32_16x16x32_bf16 v[122:125], v[154:157], v[200:203], v[122:125]
	v_mfma_f32_16x16x32_bf16 v[110:113], v[146:149], v[208:211], v[110:113]
	v_mfma_f32_16x16x32_bf16 v[106:109], v[154:157], v[208:211], v[106:109]
	v_mfma_f32_16x16x32_bf16 v[94:97], v[146:149], v[230:233], v[94:97]
	v_mfma_f32_16x16x32_bf16 v[90:93], v[154:157], v[230:233], v[90:93]
	v_mfma_f32_16x16x32_bf16 v[78:81], v[146:149], v[238:241], v[78:81]
	v_mfma_f32_16x16x32_bf16 v[74:77], v[154:157], v[238:241], v[74:77]
	s_setprio 0
	s_setprio 1
	v_mfma_f32_16x16x32_bf16 v[118:121], v[160:163], v[196:199], v[118:121]
	v_mfma_f32_16x16x32_bf16 v[114:117], v[188:191], v[196:199], v[114:117]
	v_mfma_f32_16x16x32_bf16 v[102:105], v[160:163], v[204:207], v[102:105]
	v_mfma_f32_16x16x32_bf16 v[98:101], v[188:191], v[204:207], v[98:101]
	v_mfma_f32_16x16x32_bf16 v[86:89], v[160:163], v[226:229], v[86:89]
	v_mfma_f32_16x16x32_bf16 v[82:85], v[188:191], v[226:229], v[82:85]
	v_mfma_f32_16x16x32_bf16 v[70:73], v[160:163], v[234:237], v[70:73]
	v_mfma_f32_16x16x32_bf16 v[66:69], v[188:191], v[234:237], v[66:69]
	v_mfma_f32_16x16x32_bf16 v[118:121], v[184:187], v[200:203], v[118:121]
	v_mfma_f32_16x16x32_bf16 v[114:117], v[192:195], v[200:203], v[114:117]
	v_mfma_f32_16x16x32_bf16 v[102:105], v[184:187], v[208:211], v[102:105]
	v_mfma_f32_16x16x32_bf16 v[98:101], v[192:195], v[208:211], v[98:101]
	v_mfma_f32_16x16x32_bf16 v[86:89], v[184:187], v[230:233], v[86:89]
	v_mfma_f32_16x16x32_bf16 v[82:85], v[192:195], v[230:233], v[82:85]
	v_mfma_f32_16x16x32_bf16 v[70:73], v[184:187], v[238:241], v[70:73]
	v_mfma_f32_16x16x32_bf16 v[66:69], v[192:195], v[238:241], v[66:69]
	s_setprio 0
	s_barrier
	s_add_i32 s41, s41, s49
	v_lshl_add_u64 v[168:169], s[20:21], 0, v[134:135]
	s_mov_b32 m0, s41
	ds_read_b128 v[196:199], v166 offset:16384
	ds_read_b128 v[200:203], v166 offset:17408
	ds_read_b128 v[204:207], v166 offset:18432
	ds_read_b128 v[208:211], v166 offset:19456
	ds_read_b128 v[226:229], v166 offset:20480
	ds_read_b128 v[230:233], v166 offset:21504
	ds_read_b128 v[234:237], v166 offset:22528
	ds_read_b128 v[238:241], v166 offset:23552
	global_load_lds_dwordx4 v[168:169], off
	s_add_i32 m0, s41, 0x2000
	s_add_u32 s42, s20, 0x40000
	v_lshl_add_u64 v[242:243], s[20:21], 0, v[130:131]
	s_addc_u32 s43, s21, 0
	s_add_i32 s41, s44, s49
	global_load_lds_dwordx4 v[242:243], off
	v_lshl_add_u64 v[244:245], s[42:43], 0, v[134:135]
	s_mov_b32 m0, s41
	v_lshl_add_u64 v[246:247], s[22:23], 0, v[132:133]
	global_load_lds_dwordx4 v[244:245], off
	v_lshl_add_u64 v[244:245], s[42:43], 0, v[130:131]
	s_add_i32 m0, s41, 0x2000
	s_nop 0
	global_load_lds_dwordx4 v[244:245], off
	v_lshl_add_u64 v[244:245], s[22:23], 0, v[136:137]
	s_mov_b32 m0, s50
	s_nop 0
	global_load_lds_dwordx4 v[244:245], off
	s_mov_b32 m0, s51
	s_nop 0
	global_load_lds_dwordx4 v[246:247], off
	s_waitcnt vmcnt(8)
	s_waitcnt lgkmcnt(0)
	s_barrier
	s_setprio 1
	s_waitcnt lgkmcnt(0)
	v_mfma_f32_16x16x32_bf16 v[62:65], v[142:145], v[196:199], v[62:65]
	v_mfma_f32_16x16x32_bf16 v[58:61], v[150:153], v[196:199], v[58:61]
	v_mfma_f32_16x16x32_bf16 v[46:49], v[142:145], v[204:207], v[46:49]
	v_mfma_f32_16x16x32_bf16 v[42:45], v[150:153], v[204:207], v[42:45]
	v_mfma_f32_16x16x32_bf16 v[30:33], v[142:145], v[226:229], v[30:33]
	v_mfma_f32_16x16x32_bf16 v[26:29], v[150:153], v[226:229], v[26:29]
	v_mfma_f32_16x16x32_bf16 v[14:17], v[142:145], v[234:237], v[14:17]
	v_mfma_f32_16x16x32_bf16 v[10:13], v[150:153], v[234:237], v[10:13]
	v_mfma_f32_16x16x32_bf16 v[62:65], v[146:149], v[200:203], v[62:65]
	v_mfma_f32_16x16x32_bf16 v[58:61], v[154:157], v[200:203], v[58:61]
	v_mfma_f32_16x16x32_bf16 v[46:49], v[146:149], v[208:211], v[46:49]
	v_mfma_f32_16x16x32_bf16 v[42:45], v[154:157], v[208:211], v[42:45]
	v_mfma_f32_16x16x32_bf16 v[30:33], v[146:149], v[230:233], v[30:33]
	v_mfma_f32_16x16x32_bf16 v[26:29], v[154:157], v[230:233], v[26:29]
	v_mfma_f32_16x16x32_bf16 v[14:17], v[146:149], v[238:241], v[14:17]
	v_mfma_f32_16x16x32_bf16 v[10:13], v[154:157], v[238:241], v[10:13]
	s_setprio 0
	s_setprio 1
	v_mfma_f32_16x16x32_bf16 v[54:57], v[160:163], v[196:199], v[54:57]
	v_mfma_f32_16x16x32_bf16 v[50:53], v[188:191], v[196:199], v[50:53]
	v_mfma_f32_16x16x32_bf16 v[38:41], v[160:163], v[204:207], v[38:41]
	v_mfma_f32_16x16x32_bf16 v[34:37], v[188:191], v[204:207], v[34:37]
	v_mfma_f32_16x16x32_bf16 v[22:25], v[160:163], v[226:229], v[22:25]
	v_mfma_f32_16x16x32_bf16 v[18:21], v[188:191], v[226:229], v[18:21]
	v_mfma_f32_16x16x32_bf16 v[6:9], v[160:163], v[234:237], v[6:9]
	v_mfma_f32_16x16x32_bf16 v[2:5], v[188:191], v[234:237], v[2:5]
	v_mfma_f32_16x16x32_bf16 v[54:57], v[184:187], v[200:203], v[54:57]
	v_mfma_f32_16x16x32_bf16 v[50:53], v[192:195], v[200:203], v[50:53]
	v_mfma_f32_16x16x32_bf16 v[38:41], v[184:187], v[208:211], v[38:41]
	v_mfma_f32_16x16x32_bf16 v[34:37], v[192:195], v[208:211], v[34:37]
	v_mfma_f32_16x16x32_bf16 v[22:25], v[184:187], v[230:233], v[22:25]
	v_mfma_f32_16x16x32_bf16 v[18:21], v[192:195], v[230:233], v[18:21]
	v_mfma_f32_16x16x32_bf16 v[6:9], v[184:187], v[238:241], v[6:9]
	v_mfma_f32_16x16x32_bf16 v[2:5], v[192:195], v[238:241], v[2:5]
	s_setprio 0
	s_barrier
	s_add_i32 s41, 0, 0x18000
	v_add_u32_e32 v0, s41, v165
	s_add_i32 s42, 0, 0x1c000
	ds_read_b128 v[142:145], v0
	ds_read_b128 v[146:149], v0 offset:1024
	ds_read_b128 v[150:153], v0 offset:2048
	ds_read_b128 v[154:157], v0 offset:3072
	v_add_u32_e32 v0, s42, v165
	ds_read_b128 v[160:163], v0
	ds_read_b128 v[184:187], v0 offset:1024
	ds_read_b128 v[188:191], v0 offset:2048
	ds_read_b128 v[192:195], v0 offset:3072
	s_add_u32 s22, s22, 0x40000
	s_addc_u32 s23, s23, 0
	s_mov_b32 m0, s52
	v_lshl_add_u64 v[248:249], s[22:23], 0, v[136:137]
	ds_read_b128 v[196:199], v166 offset:32768
	ds_read_b128 v[200:203], v166 offset:33792
	ds_read_b128 v[204:207], v166 offset:34816
	ds_read_b128 v[208:211], v166 offset:35840
	ds_read_b128 v[226:229], v166 offset:36864
	ds_read_b128 v[230:233], v166 offset:37888
	ds_read_b128 v[234:237], v166 offset:38912
	ds_read_b128 v[238:241], v166 offset:39936
	global_load_lds_dwordx4 v[248:249], off
	v_lshl_add_u64 v[248:249], s[22:23], 0, v[132:133]
	s_mov_b32 m0, s53
	s_nop 0
	global_load_lds_dwordx4 v[248:249], off
	s_waitcnt vmcnt(8)
	s_waitcnt lgkmcnt(0)
	s_barrier
	s_setprio 1
	s_waitcnt lgkmcnt(0)
	v_mfma_f32_16x16x32_bf16 v[126:129], v[142:145], v[196:199], v[126:129]
	v_mfma_f32_16x16x32_bf16 v[122:125], v[150:153], v[196:199], v[122:125]
	v_mfma_f32_16x16x32_bf16 v[110:113], v[142:145], v[204:207], v[110:113]
	v_mfma_f32_16x16x32_bf16 v[106:109], v[150:153], v[204:207], v[106:109]
	v_mfma_f32_16x16x32_bf16 v[94:97], v[142:145], v[226:229], v[94:97]
	v_mfma_f32_16x16x32_bf16 v[90:93], v[150:153], v[226:229], v[90:93]
	v_mfma_f32_16x16x32_bf16 v[78:81], v[142:145], v[234:237], v[78:81]
	v_mfma_f32_16x16x32_bf16 v[74:77], v[150:153], v[234:237], v[74:77]
	v_mfma_f32_16x16x32_bf16 v[126:129], v[146:149], v[200:203], v[126:129]
	v_mfma_f32_16x16x32_bf16 v[122:125], v[154:157], v[200:203], v[122:125]
	v_mfma_f32_16x16x32_bf16 v[110:113], v[146:149], v[208:211], v[110:113]
	v_mfma_f32_16x16x32_bf16 v[106:109], v[154:157], v[208:211], v[106:109]
	v_mfma_f32_16x16x32_bf16 v[94:97], v[146:149], v[230:233], v[94:97]
	v_mfma_f32_16x16x32_bf16 v[90:93], v[154:157], v[230:233], v[90:93]
	v_mfma_f32_16x16x32_bf16 v[78:81], v[146:149], v[238:241], v[78:81]
	v_mfma_f32_16x16x32_bf16 v[74:77], v[154:157], v[238:241], v[74:77]
	s_setprio 0
	s_setprio 1
	v_mfma_f32_16x16x32_bf16 v[118:121], v[160:163], v[196:199], v[118:121]
	v_mfma_f32_16x16x32_bf16 v[114:117], v[188:191], v[196:199], v[114:117]
	v_mfma_f32_16x16x32_bf16 v[102:105], v[160:163], v[204:207], v[102:105]
	v_mfma_f32_16x16x32_bf16 v[98:101], v[188:191], v[204:207], v[98:101]
	v_mfma_f32_16x16x32_bf16 v[86:89], v[160:163], v[226:229], v[86:89]
	v_mfma_f32_16x16x32_bf16 v[82:85], v[188:191], v[226:229], v[82:85]
	v_mfma_f32_16x16x32_bf16 v[70:73], v[160:163], v[234:237], v[70:73]
	v_mfma_f32_16x16x32_bf16 v[66:69], v[188:191], v[234:237], v[66:69]
	v_mfma_f32_16x16x32_bf16 v[118:121], v[184:187], v[200:203], v[118:121]
	v_mfma_f32_16x16x32_bf16 v[114:117], v[192:195], v[200:203], v[114:117]
	v_mfma_f32_16x16x32_bf16 v[102:105], v[184:187], v[208:211], v[102:105]
	v_mfma_f32_16x16x32_bf16 v[98:101], v[192:195], v[208:211], v[98:101]
	v_mfma_f32_16x16x32_bf16 v[86:89], v[184:187], v[230:233], v[86:89]
	v_mfma_f32_16x16x32_bf16 v[82:85], v[192:195], v[230:233], v[82:85]
	v_mfma_f32_16x16x32_bf16 v[70:73], v[184:187], v[238:241], v[70:73]
	v_mfma_f32_16x16x32_bf16 v[66:69], v[192:195], v[238:241], v[66:69]
	s_setprio 0
	s_barrier
	s_add_i32 s22, s41, s49
	v_lshl_add_u64 v[168:169], v[168:169], 0, s[14:15]
	s_mov_b32 m0, s22
	ds_read_b128 v[196:199], v166 offset:49152
	ds_read_b128 v[200:203], v166 offset:50176
	ds_read_b128 v[204:207], v166 offset:51200
	ds_read_b128 v[208:211], v166 offset:52224
	ds_read_b128 v[226:229], v166 offset:53248
	ds_read_b128 v[230:233], v166 offset:54272
	ds_read_b128 v[234:237], v166 offset:55296
	ds_read_b128 v[238:241], v166 offset:56320
	global_load_lds_dwordx4 v[168:169], off
	s_add_i32 m0, s22, 0x2000
	s_add_u32 s20, s20, 0x40080
	v_lshl_add_u64 v[168:169], v[242:243], 0, s[14:15]
	s_addc_u32 s21, s21, 0
	s_add_i32 s22, s42, s49
	global_load_lds_dwordx4 v[168:169], off
	v_lshl_add_u64 v[168:169], s[20:21], 0, v[134:135]
	s_mov_b32 m0, s22
	s_nop 0
	global_load_lds_dwordx4 v[168:169], off
	v_lshl_add_u64 v[168:169], s[20:21], 0, v[130:131]
	s_add_i32 m0, s22, 0x2000
	s_nop 0
	global_load_lds_dwordx4 v[168:169], off
	v_lshl_add_u64 v[168:169], v[244:245], 0, s[14:15]
	s_mov_b32 m0, s60
	s_nop 0
	global_load_lds_dwordx4 v[168:169], off
	v_lshl_add_u64 v[168:169], v[246:247], 0, s[14:15]
	s_mov_b32 m0, s61
	s_nop 0
	global_load_lds_dwordx4 v[168:169], off
	s_waitcnt vmcnt(8)
	s_waitcnt lgkmcnt(0)
	s_barrier
	s_setprio 1
	s_waitcnt lgkmcnt(0)
	v_mfma_f32_16x16x32_bf16 v[62:65], v[142:145], v[196:199], v[62:65]
	v_mfma_f32_16x16x32_bf16 v[58:61], v[150:153], v[196:199], v[58:61]
	v_mfma_f32_16x16x32_bf16 v[46:49], v[142:145], v[204:207], v[46:49]
	v_mfma_f32_16x16x32_bf16 v[42:45], v[150:153], v[204:207], v[42:45]
	v_mfma_f32_16x16x32_bf16 v[30:33], v[142:145], v[226:229], v[30:33]
	v_mfma_f32_16x16x32_bf16 v[26:29], v[150:153], v[226:229], v[26:29]
	v_mfma_f32_16x16x32_bf16 v[14:17], v[142:145], v[234:237], v[14:17]
	v_mfma_f32_16x16x32_bf16 v[10:13], v[150:153], v[234:237], v[10:13]
	v_mfma_f32_16x16x32_bf16 v[62:65], v[146:149], v[200:203], v[62:65]
	v_mfma_f32_16x16x32_bf16 v[58:61], v[154:157], v[200:203], v[58:61]
	v_mfma_f32_16x16x32_bf16 v[46:49], v[146:149], v[208:211], v[46:49]
	v_mfma_f32_16x16x32_bf16 v[42:45], v[154:157], v[208:211], v[42:45]
	v_mfma_f32_16x16x32_bf16 v[30:33], v[146:149], v[230:233], v[30:33]
	v_mfma_f32_16x16x32_bf16 v[26:29], v[154:157], v[230:233], v[26:29]
	v_mfma_f32_16x16x32_bf16 v[14:17], v[146:149], v[238:241], v[14:17]
	v_mfma_f32_16x16x32_bf16 v[10:13], v[154:157], v[238:241], v[10:13]
	s_setprio 0
	s_setprio 1
	v_mfma_f32_16x16x32_bf16 v[54:57], v[160:163], v[196:199], v[54:57]
	v_mfma_f32_16x16x32_bf16 v[50:53], v[188:191], v[196:199], v[50:53]
	v_mfma_f32_16x16x32_bf16 v[38:41], v[160:163], v[204:207], v[38:41]
	v_mfma_f32_16x16x32_bf16 v[34:37], v[188:191], v[204:207], v[34:37]
	v_mfma_f32_16x16x32_bf16 v[22:25], v[160:163], v[226:229], v[22:25]
	v_mfma_f32_16x16x32_bf16 v[18:21], v[188:191], v[226:229], v[18:21]
	v_mfma_f32_16x16x32_bf16 v[6:9], v[160:163], v[234:237], v[6:9]
	v_mfma_f32_16x16x32_bf16 v[2:5], v[188:191], v[234:237], v[2:5]
	v_mfma_f32_16x16x32_bf16 v[54:57], v[184:187], v[200:203], v[54:57]
	v_mfma_f32_16x16x32_bf16 v[50:53], v[192:195], v[200:203], v[50:53]
	v_mfma_f32_16x16x32_bf16 v[38:41], v[184:187], v[208:211], v[38:41]
	v_mfma_f32_16x16x32_bf16 v[34:37], v[192:195], v[208:211], v[34:37]
	v_mfma_f32_16x16x32_bf16 v[22:25], v[184:187], v[230:233], v[22:25]
	v_mfma_f32_16x16x32_bf16 v[18:21], v[192:195], v[230:233], v[18:21]
	v_mfma_f32_16x16x32_bf16 v[6:9], v[184:187], v[238:241], v[6:9]
	v_mfma_f32_16x16x32_bf16 v[2:5], v[192:195], v[238:241], v[2:5]
	s_setprio 0
	s_add_i32 s40, s40, 2
	s_add_u32 s18, s18, 0x100
	s_addc_u32 s19, s19, 0
	s_add_u32 s38, s38, 0x100
	s_addc_u32 s39, s39, 0
	s_add_u32 s20, s18, 0xfffc0080
	s_addc_u32 s21, s19, -1
	s_add_i32 s41, 0, 0x10000
	s_cmp_eq_u32 s40, 12
	s_cselect_b32 s23, s9, s21
	s_cselect_b32 s22, s25, s20
	s_cselect_b32 s21, s11, s39
	s_cselect_b32 s20, s34, s38
	s_add_i32 s44, 0, 0x14000
	s_barrier
	s_cmp_gt_u32 s40, 13
	s_cbranch_scc0 .Lrot_498
	s_and_b64 vcc, exec, s[4:5]
	s_cbranch_vccz .LBB0_501
	s_barrier

.LBB0_748:
	s_add_u32 s20, s18, 0xfffc0080
	s_addc_u32 s21, s19, -1
	s_add_i32 s43, 0, 0x10000
	s_cmp_eq_u32 s42, 12
	s_cselect_b32 s23, s9, s21
	s_cselect_b32 s22, s25, s20
	s_cselect_b32 s21, s11, s41
	s_cselect_b32 s20, s34, s40
	s_add_i32 s62, 0, 0x14000
.Lrot_748:
	v_add_u32_e32 v0, s43, v199
	ds_read_b128 v[142:145], v0
	ds_read_b128 v[146:149], v0 offset:1024
	ds_read_b128 v[150:153], v0 offset:2048
	ds_read_b128 v[154:157], v0 offset:3072
	v_add_u32_e32 v0, s62, v199
	ds_read_b128 v[158:161], v0
	ds_read_b128 v[162:165], v0 offset:1024
	ds_read_b128 v[166:169], v0 offset:2048
	ds_read_b128 v[184:187], v0 offset:3072
	v_lshl_add_u64 v[210:211], s[18:19], 0, v[138:139]
	s_add_i32 m0, s49, 0xc000
	ds_read_b128 v[188:191], v200
	ds_read_b128 v[192:195], v200 offset:1024
	ds_read_b128 v[202:205], v200 offset:2048
	ds_read_b128 v[206:209], v200 offset:3072
	ds_read_b128 v[226:229], v200 offset:4096
	ds_read_b128 v[230:233], v200 offset:5120
	ds_read_b128 v[234:237], v200 offset:6144
	ds_read_b128 v[238:241], v200 offset:7168
	global_load_lds_dwordx4 v[210:211], off
	v_lshl_add_u64 v[210:211], s[18:19], 0, v[140:141]
	s_add_i32 m0, s49, 0xe000
	s_nop 0
	global_load_lds_dwordx4 v[210:211], off
	s_waitcnt vmcnt(8)
	s_waitcnt lgkmcnt(0)
	s_barrier
	s_setprio 1
	s_waitcnt lgkmcnt(0)
	v_mfma_f32_16x16x32_bf16 v[126:129], v[142:145], v[188:191], v[126:129]
	v_mfma_f32_16x16x32_bf16 v[122:125], v[150:153], v[188:191], v[122:125]
	v_mfma_f32_16x16x32_bf16 v[110:113], v[142:145], v[202:205], v[110:113]
	v_mfma_f32_16x16x32_bf16 v[106:109], v[150:153], v[202:205], v[106:109]
	v_mfma_f32_16x16x32_bf16 v[94:97], v[142:145], v[226:229], v[94:97]
	v_mfma_f32_16x16x32_bf16 v[90:93], v[150:153], v[226:229], v[90:93]
	v_mfma_f32_16x16x32_bf16 v[78:81], v[142:145], v[234:237], v[78:81]
	v_mfma_f32_16x16x32_bf16 v[74:77], v[150:153], v[234:237], v[74:77]
	v_mfma_f32_16x16x32_bf16 v[126:129], v[146:149], v[192:195], v[126:129]
	v_mfma_f32_16x16x32_bf16 v[122:125], v[154:157], v[192:195], v[122:125]
	v_mfma_f32_16x16x32_bf16 v[110:113], v[146:149], v[206:209], v[110:113]
	v_mfma_f32_16x16x32_bf16 v[106:109], v[154:157], v[206:209], v[106:109]
	v_mfma_f32_16x16x32_bf16 v[94:97], v[146:149], v[230:233], v[94:97]
	v_mfma_f32_16x16x32_bf16 v[90:93], v[154:157], v[230:233], v[90:93]
	v_mfma_f32_16x16x32_bf16 v[78:81], v[146:149], v[238:241], v[78:81]
	v_mfma_f32_16x16x32_bf16 v[74:77], v[154:157], v[238:241], v[74:77]
	s_setprio 0
	s_setprio 1
	v_mfma_f32_16x16x32_bf16 v[118:121], v[158:161], v[188:191], v[118:121]
	v_mfma_f32_16x16x32_bf16 v[114:117], v[166:169], v[188:191], v[114:117]
	v_mfma_f32_16x16x32_bf16 v[102:105], v[158:161], v[202:205], v[102:105]
	v_mfma_f32_16x16x32_bf16 v[98:101], v[166:169], v[202:205], v[98:101]
	v_mfma_f32_16x16x32_bf16 v[86:89], v[158:161], v[226:229], v[86:89]
	v_mfma_f32_16x16x32_bf16 v[82:85], v[166:169], v[226:229], v[82:85]
	v_mfma_f32_16x16x32_bf16 v[70:73], v[158:161], v[234:237], v[70:73]
	v_mfma_f32_16x16x32_bf16 v[66:69], v[166:169], v[234:237], v[66:69]
	v_mfma_f32_16x16x32_bf16 v[118:121], v[162:165], v[192:195], v[118:121]
	v_mfma_f32_16x16x32_bf16 v[114:117], v[184:187], v[192:195], v[114:117]
	v_mfma_f32_16x16x32_bf16 v[102:105], v[162:165], v[206:209], v[102:105]
	v_mfma_f32_16x16x32_bf16 v[98:101], v[184:187], v[206:209], v[98:101]
	v_mfma_f32_16x16x32_bf16 v[86:89], v[162:165], v[230:233], v[86:89]
	v_mfma_f32_16x16x32_bf16 v[82:85], v[184:187], v[230:233], v[82:85]
	v_mfma_f32_16x16x32_bf16 v[70:73], v[162:165], v[238:241], v[70:73]
	v_mfma_f32_16x16x32_bf16 v[66:69], v[184:187], v[238:241], v[66:69]
	s_setprio 0
	s_barrier
	s_add_i32 s43, s43, s1
	v_lshl_add_u64 v[210:211], s[20:21], 0, v[134:135]
	s_mov_b32 m0, s43
	ds_read_b128 v[188:191], v200 offset:16384
	ds_read_b128 v[192:195], v200 offset:17408
	ds_read_b128 v[202:205], v200 offset:18432
	ds_read_b128 v[206:209], v200 offset:19456
	ds_read_b128 v[226:229], v200 offset:20480
	ds_read_b128 v[230:233], v200 offset:21504
	ds_read_b128 v[234:237], v200 offset:22528
	ds_read_b128 v[238:241], v200 offset:23552
	global_load_lds_dwordx4 v[210:211], off
	s_add_i32 m0, s43, 0x2000
	s_add_u32 s44, s20, 0x40000
	v_lshl_add_u64 v[242:243], s[20:21], 0, v[130:131]
	s_addc_u32 s45, s21, 0
	s_add_i32 s43, s62, s1
	global_load_lds_dwordx4 v[242:243], off
	v_lshl_add_u64 v[244:245], s[44:45], 0, v[134:135]
	s_mov_b32 m0, s43
	v_lshl_add_u64 v[246:247], s[22:23], 0, v[132:133]
	global_load_lds_dwordx4 v[244:245], off
	v_lshl_add_u64 v[244:245], s[44:45], 0, v[130:131]
	s_add_i32 m0, s43, 0x2000
	s_nop 0
	global_load_lds_dwordx4 v[244:245], off
	v_lshl_add_u64 v[244:245], s[22:23], 0, v[136:137]
	s_mov_b32 m0, s49
	s_nop 0
	global_load_lds_dwordx4 v[244:245], off
	s_mov_b32 m0, s50
	s_nop 0
	global_load_lds_dwordx4 v[246:247], off
	s_waitcnt vmcnt(8)
	s_waitcnt lgkmcnt(0)
	s_barrier
	s_setprio 1
	s_waitcnt lgkmcnt(0)
	v_mfma_f32_16x16x32_bf16 v[62:65], v[142:145], v[188:191], v[62:65]
	v_mfma_f32_16x16x32_bf16 v[58:61], v[150:153], v[188:191], v[58:61]
	v_mfma_f32_16x16x32_bf16 v[46:49], v[142:145], v[202:205], v[46:49]
	v_mfma_f32_16x16x32_bf16 v[42:45], v[150:153], v[202:205], v[42:45]
	v_mfma_f32_16x16x32_bf16 v[30:33], v[142:145], v[226:229], v[30:33]
	v_mfma_f32_16x16x32_bf16 v[26:29], v[150:153], v[226:229], v[26:29]
	v_mfma_f32_16x16x32_bf16 v[14:17], v[142:145], v[234:237], v[14:17]
	v_mfma_f32_16x16x32_bf16 v[10:13], v[150:153], v[234:237], v[10:13]
	v_mfma_f32_16x16x32_bf16 v[62:65], v[146:149], v[192:195], v[62:65]
	v_mfma_f32_16x16x32_bf16 v[58:61], v[154:157], v[192:195], v[58:61]
	v_mfma_f32_16x16x32_bf16 v[46:49], v[146:149], v[206:209], v[46:49]
	v_mfma_f32_16x16x32_bf16 v[42:45], v[154:157], v[206:209], v[42:45]
	v_mfma_f32_16x16x32_bf16 v[30:33], v[146:149], v[230:233], v[30:33]
	v_mfma_f32_16x16x32_bf16 v[26:29], v[154:157], v[230:233], v[26:29]
	v_mfma_f32_16x16x32_bf16 v[14:17], v[146:149], v[238:241], v[14:17]
	v_mfma_f32_16x16x32_bf16 v[10:13], v[154:157], v[238:241], v[10:13]
	s_setprio 0
	s_setprio 1
	v_mfma_f32_16x16x32_bf16 v[54:57], v[158:161], v[188:191], v[54:57]
	v_mfma_f32_16x16x32_bf16 v[50:53], v[166:169], v[188:191], v[50:53]
	v_mfma_f32_16x16x32_bf16 v[38:41], v[158:161], v[202:205], v[38:41]
	v_mfma_f32_16x16x32_bf16 v[34:37], v[166:169], v[202:205], v[34:37]
	v_mfma_f32_16x16x32_bf16 v[22:25], v[158:161], v[226:229], v[22:25]
	v_mfma_f32_16x16x32_bf16 v[18:21], v[166:169], v[226:229], v[18:21]
	v_mfma_f32_16x16x32_bf16 v[6:9], v[158:161], v[234:237], v[6:9]
	v_mfma_f32_16x16x32_bf16 v[2:5], v[166:169], v[234:237], v[2:5]
	v_mfma_f32_16x16x32_bf16 v[54:57], v[162:165], v[192:195], v[54:57]
	v_mfma_f32_16x16x32_bf16 v[50:53], v[184:187], v[192:195], v[50:53]
	v_mfma_f32_16x16x32_bf16 v[38:41], v[162:165], v[206:209], v[38:41]
	v_mfma_f32_16x16x32_bf16 v[34:37], v[184:187], v[206:209], v[34:37]
	v_mfma_f32_16x16x32_bf16 v[22:25], v[162:165], v[230:233], v[22:25]
	v_mfma_f32_16x16x32_bf16 v[18:21], v[184:187], v[230:233], v[18:21]
	v_mfma_f32_16x16x32_bf16 v[6:9], v[162:165], v[238:241], v[6:9]
	v_mfma_f32_16x16x32_bf16 v[2:5], v[184:187], v[238:241], v[2:5]
	s_setprio 0
	s_barrier
	s_add_i32 s43, 0, 0x18000
	v_add_u32_e32 v0, s43, v199
	s_add_i32 s44, 0, 0x1c000
	ds_read_b128 v[142:145], v0
	ds_read_b128 v[146:149], v0 offset:1024
	ds_read_b128 v[150:153], v0 offset:2048
	ds_read_b128 v[154:157], v0 offset:3072
	v_add_u32_e32 v0, s44, v199
	ds_read_b128 v[158:161], v0
	ds_read_b128 v[162:165], v0 offset:1024
	ds_read_b128 v[166:169], v0 offset:2048
	ds_read_b128 v[184:187], v0 offset:3072
	s_add_u32 s22, s22, 0x40000
	s_addc_u32 s23, s23, 0
	s_mov_b32 m0, s51
	v_lshl_add_u64 v[248:249], s[22:23], 0, v[136:137]
	ds_read_b128 v[188:191], v200 offset:32768
	ds_read_b128 v[192:195], v200 offset:33792
	ds_read_b128 v[202:205], v200 offset:34816
	ds_read_b128 v[206:209], v200 offset:35840
	ds_read_b128 v[226:229], v200 offset:36864
	ds_read_b128 v[230:233], v200 offset:37888
	ds_read_b128 v[234:237], v200 offset:38912
	ds_read_b128 v[238:241], v200 offset:39936
	global_load_lds_dwordx4 v[248:249], off
	v_lshl_add_u64 v[248:249], s[22:23], 0, v[132:133]
	s_mov_b32 m0, s52
	s_nop 0
	global_load_lds_dwordx4 v[248:249], off
	s_waitcnt vmcnt(8)
	s_waitcnt lgkmcnt(0)
	s_barrier
	s_setprio 1
	s_waitcnt lgkmcnt(0)
	v_mfma_f32_16x16x32_bf16 v[126:129], v[142:145], v[188:191], v[126:129]
	v_mfma_f32_16x16x32_bf16 v[122:125], v[150:153], v[188:191], v[122:125]
	v_mfma_f32_16x16x32_bf16 v[110:113], v[142:145], v[202:205], v[110:113]
	v_mfma_f32_16x16x32_bf16 v[106:109], v[150:153], v[202:205], v[106:109]
	v_mfma_f32_16x16x32_bf16 v[94:97], v[142:145], v[226:229], v[94:97]
	v_mfma_f32_16x16x32_bf16 v[90:93], v[150:153], v[226:229], v[90:93]
	v_mfma_f32_16x16x32_bf16 v[78:81], v[142:145], v[234:237], v[78:81]
	v_mfma_f32_16x16x32_bf16 v[74:77], v[150:153], v[234:237], v[74:77]
	v_mfma_f32_16x16x32_bf16 v[126:129], v[146:149], v[192:195], v[126:129]
	v_mfma_f32_16x16x32_bf16 v[122:125], v[154:157], v[192:195], v[122:125]
	v_mfma_f32_16x16x32_bf16 v[110:113], v[146:149], v[206:209], v[110:113]
	v_mfma_f32_16x16x32_bf16 v[106:109], v[154:157], v[206:209], v[106:109]
	v_mfma_f32_16x16x32_bf16 v[94:97], v[146:149], v[230:233], v[94:97]
	v_mfma_f32_16x16x32_bf16 v[90:93], v[154:157], v[230:233], v[90:93]
	v_mfma_f32_16x16x32_bf16 v[78:81], v[146:149], v[238:241], v[78:81]
	v_mfma_f32_16x16x32_bf16 v[74:77], v[154:157], v[238:241], v[74:77]
	s_setprio 0
	s_setprio 1
	v_mfma_f32_16x16x32_bf16 v[118:121], v[158:161], v[188:191], v[118:121]
	v_mfma_f32_16x16x32_bf16 v[114:117], v[166:169], v[188:191], v[114:117]
	v_mfma_f32_16x16x32_bf16 v[102:105], v[158:161], v[202:205], v[102:105]
	v_mfma_f32_16x16x32_bf16 v[98:101], v[166:169], v[202:205], v[98:101]
	v_mfma_f32_16x16x32_bf16 v[86:89], v[158:161], v[226:229], v[86:89]
	v_mfma_f32_16x16x32_bf16 v[82:85], v[166:169], v[226:229], v[82:85]
	v_mfma_f32_16x16x32_bf16 v[70:73], v[158:161], v[234:237], v[70:73]
	v_mfma_f32_16x16x32_bf16 v[66:69], v[166:169], v[234:237], v[66:69]
	v_mfma_f32_16x16x32_bf16 v[118:121], v[162:165], v[192:195], v[118:121]
	v_mfma_f32_16x16x32_bf16 v[114:117], v[184:187], v[192:195], v[114:117]
	v_mfma_f32_16x16x32_bf16 v[102:105], v[162:165], v[206:209], v[102:105]
	v_mfma_f32_16x16x32_bf16 v[98:101], v[184:187], v[206:209], v[98:101]
	v_mfma_f32_16x16x32_bf16 v[86:89], v[162:165], v[230:233], v[86:89]
	v_mfma_f32_16x16x32_bf16 v[82:85], v[184:187], v[230:233], v[82:85]
	v_mfma_f32_16x16x32_bf16 v[70:73], v[162:165], v[238:241], v[70:73]
	v_mfma_f32_16x16x32_bf16 v[66:69], v[184:187], v[238:241], v[66:69]
	s_setprio 0
	s_barrier
	s_add_i32 s22, s43, s1
	v_lshl_add_u64 v[210:211], v[210:211], 0, s[14:15]
	s_mov_b32 m0, s22
	ds_read_b128 v[188:191], v200 offset:49152
	ds_read_b128 v[192:195], v200 offset:50176
	ds_read_b128 v[202:205], v200 offset:51200
	ds_read_b128 v[206:209], v200 offset:52224
	ds_read_b128 v[226:229], v200 offset:53248
	ds_read_b128 v[230:233], v200 offset:54272
	ds_read_b128 v[234:237], v200 offset:55296
	ds_read_b128 v[238:241], v200 offset:56320
	global_load_lds_dwordx4 v[210:211], off
	s_add_i32 m0, s22, 0x2000
	s_add_u32 s20, s20, 0x40080
	v_lshl_add_u64 v[210:211], v[242:243], 0, s[14:15]
	s_addc_u32 s21, s21, 0
	s_add_i32 s22, s44, s1
	global_load_lds_dwordx4 v[210:211], off
	v_lshl_add_u64 v[210:211], s[20:21], 0, v[134:135]
	s_mov_b32 m0, s22
	s_nop 0
	global_load_lds_dwordx4 v[210:211], off
	v_lshl_add_u64 v[210:211], s[20:21], 0, v[130:131]
	s_add_i32 m0, s22, 0x2000
	s_nop 0
	global_load_lds_dwordx4 v[210:211], off
	v_lshl_add_u64 v[210:211], v[244:245], 0, s[14:15]
	s_mov_b32 m0, s55
	s_nop 0
	global_load_lds_dwordx4 v[210:211], off
	v_lshl_add_u64 v[210:211], v[246:247], 0, s[14:15]
	s_mov_b32 m0, s56
	s_nop 0
	global_load_lds_dwordx4 v[210:211], off
	s_waitcnt vmcnt(8)
	s_waitcnt lgkmcnt(0)
	s_barrier
	s_setprio 1
	s_waitcnt lgkmcnt(0)
	v_mfma_f32_16x16x32_bf16 v[62:65], v[142:145], v[188:191], v[62:65]
	v_mfma_f32_16x16x32_bf16 v[58:61], v[150:153], v[188:191], v[58:61]
	v_mfma_f32_16x16x32_bf16 v[46:49], v[142:145], v[202:205], v[46:49]
	v_mfma_f32_16x16x32_bf16 v[42:45], v[150:153], v[202:205], v[42:45]
	v_mfma_f32_16x16x32_bf16 v[30:33], v[142:145], v[226:229], v[30:33]
	v_mfma_f32_16x16x32_bf16 v[26:29], v[150:153], v[226:229], v[26:29]
	v_mfma_f32_16x16x32_bf16 v[14:17], v[142:145], v[234:237], v[14:17]
	v_mfma_f32_16x16x32_bf16 v[10:13], v[150:153], v[234:237], v[10:13]
	v_mfma_f32_16x16x32_bf16 v[62:65], v[146:149], v[192:195], v[62:65]
	v_mfma_f32_16x16x32_bf16 v[58:61], v[154:157], v[192:195], v[58:61]
	v_mfma_f32_16x16x32_bf16 v[46:49], v[146:149], v[206:209], v[46:49]
	v_mfma_f32_16x16x32_bf16 v[42:45], v[154:157], v[206:209], v[42:45]
	v_mfma_f32_16x16x32_bf16 v[30:33], v[146:149], v[230:233], v[30:33]
	v_mfma_f32_16x16x32_bf16 v[26:29], v[154:157], v[230:233], v[26:29]
	v_mfma_f32_16x16x32_bf16 v[14:17], v[146:149], v[238:241], v[14:17]
	v_mfma_f32_16x16x32_bf16 v[10:13], v[154:157], v[238:241], v[10:13]
	s_setprio 0
	s_setprio 1
	v_mfma_f32_16x16x32_bf16 v[54:57], v[158:161], v[188:191], v[54:57]
	v_mfma_f32_16x16x32_bf16 v[50:53], v[166:169], v[188:191], v[50:53]
	v_mfma_f32_16x16x32_bf16 v[38:41], v[158:161], v[202:205], v[38:41]
	v_mfma_f32_16x16x32_bf16 v[34:37], v[166:169], v[202:205], v[34:37]
	v_mfma_f32_16x16x32_bf16 v[22:25], v[158:161], v[226:229], v[22:25]
	v_mfma_f32_16x16x32_bf16 v[18:21], v[166:169], v[226:229], v[18:21]
	v_mfma_f32_16x16x32_bf16 v[6:9], v[158:161], v[234:237], v[6:9]
	v_mfma_f32_16x16x32_bf16 v[2:5], v[166:169], v[234:237], v[2:5]
	v_mfma_f32_16x16x32_bf16 v[54:57], v[162:165], v[192:195], v[54:57]
	v_mfma_f32_16x16x32_bf16 v[50:53], v[184:187], v[192:195], v[50:53]
	v_mfma_f32_16x16x32_bf16 v[38:41], v[162:165], v[206:209], v[38:41]
	v_mfma_f32_16x16x32_bf16 v[34:37], v[184:187], v[206:209], v[34:37]
	v_mfma_f32_16x16x32_bf16 v[22:25], v[162:165], v[230:233], v[22:25]
	v_mfma_f32_16x16x32_bf16 v[18:21], v[184:187], v[230:233], v[18:21]
	v_mfma_f32_16x16x32_bf16 v[6:9], v[162:165], v[238:241], v[6:9]
	v_mfma_f32_16x16x32_bf16 v[2:5], v[184:187], v[238:241], v[2:5]
	s_setprio 0
	s_add_i32 s42, s42, 2
	s_add_u32 s18, s18, 0x100
	s_addc_u32 s19, s19, 0
	s_add_u32 s40, s40, 0x100
	s_addc_u32 s41, s41, 0
	s_add_u32 s20, s18, 0xfffc0080
	s_addc_u32 s21, s19, -1
	s_add_i32 s43, 0, 0x10000
	s_cmp_eq_u32 s42, 12
	s_cselect_b32 s23, s9, s21
	s_cselect_b32 s22, s25, s20
	s_cselect_b32 s21, s11, s41
	s_cselect_b32 s20, s34, s40
	s_add_i32 s62, 0, 0x14000
	s_barrier
	s_cmp_gt_u32 s42, 13
	s_cbranch_scc0 .Lrot_748
	s_and_b64 vcc, exec, s[6:7]
	s_cbranch_vccz .LBB0_751
	s_barrier
